# v17 + SwiGLU epilogue pk_mul/mov cleanup + MLA loop trims: LDS-DMA m0 computed on the SALU from the wave id, zero-offset 64-bit address copies removed, redundant max canonicalisation removed
# speedup vs baseline: 1.0114x; 1.0114x over previous
; DI void finishSM(f32x16& p0, f32x16& p1, float alpha, float& l_reg, bf16x8& pa0, bf16x8& pa1, bf16x8& pa2, bf16x8& pa3) {
; #pragma unroll
;   for (int r = 0; r < 16; ++r) p1[r] = __builtin_amdgcn_exp2f(p1[r]);
;   float ps = 0;
; #pragma unroll
;   for (int r = 0; r < 16; ++r) ps += p0[r];
; #pragma unroll
;   for (int r = 0; r < 16; ++r) ps += p1[r];
;   { auto rr = __builtin_amdgcn_permlane32_swap(__float_as_uint(ps), __float_as_uint(ps), false, false);
;     ps = __uint_as_float(rr[0]) + __uint_as_float(rr[1]); }
;   l_reg = l_reg * alpha + ps;
;   PK4(p0, 0, pa0); PK4(p0, 8, pa1); PK4(p1, 0, pa2); PK4(p1, 8, pa3);
; }
; template <int NPE>
; DI void qkt_r(f32x16& p0, f32x16& p1, const char* Ks, const char* Ps, const bf16x8* qr, int r32, int hi) {
;   p0 = f32x16{}; p1 = f32x16{};
; #pragma unroll
;   for (int d0 = 0; d0 < 8; ++d0) { int cb = (d0 * 16 + hi * 8) * 2;
;     bf16x8 b0 = *reinterpret_cast<const bf16x8*>(Ks + KSWZ(r32, cb));
;     bf16x8 b1 = *reinterpret_cast<const bf16x8*>(Ks + KSWZ(32 + r32, cb));
;     p0 = __builtin_amdgcn_mfma_f32_32x32x16_bf16(b0, qr[d0], p0, 0, 0, 0);
;     p1 = __builtin_amdgcn_mfma_f32_32x32x16_bf16(b1, qr[d0], p1, 0, 0, 0); }
; #pragma unroll
;   for (int d0 = 0; d0 < NPE; ++d0) { int cb = (d0 * 16 + hi * 8) * 2;
;     bf16x8 b0 = *reinterpret_cast<const bf16x8*>(Ps + PSWZ(r32, cb));
;     bf16x8 b1 = *reinterpret_cast<const bf16x8*>(Ps + PSWZ(32 + r32, cb));
;     p0 = __builtin_amdgcn_mfma_f32_32x32x16_bf16(b0, qr[8 + d0], p0, 0, 0, 0);
;     p1 = __builtin_amdgcn_mfma_f32_32x32x16_bf16(b1, qr[8 + d0], p1, 0, 0, 0); }
; }
.LBB0_928:
	s_mov_b32 s63, s1
	v_exp_f32_e32 v160, v185
	v_add_u32_e32 v68, s63, v188
	v_add_u32_e32 v243, s63, v191
	ds_read_b128 v[64:67], v68 offset:16384
	ds_read_b128 v[244:247], v243 offset:16384
	v_add_u32_e32 v252, s63, v194
	v_add_u32_e32 v253, s63, v197
	ds_read_b128 v[226:229], v252 offset:16384
	v_add_u32_e32 v144, s63, v200
	ds_read_b128 v[68:71], v68 offset:24576
	ds_read_b128 v[248:251], v243 offset:24576
	v_add_u32_e32 v243, s63, v203
	ds_read_b128 v[230:233], v252 offset:24576
	v_add_u32_e32 v252, s63, v205
	v_exp_f32_e32 v182, v182
	v_exp_f32_e32 v183, v183
	v_exp_f32_e32 v180, v180
	v_exp_f32_e32 v181, v181
	v_exp_f32_e32 v178, v178
	v_exp_f32_e32 v179, v179
	s_mov_b32 s1, s2
	v_exp_f32_e32 v185, v177
	v_cvt_pk_bf16_f32 v177, v162, v164
	v_exp_f32_e32 v215, v175
	v_cvt_pk_bf16_f32 v175, v166, v168
	v_exp_f32_e32 v186, v174
	v_exp_f32_e32 v216, v172
	v_exp_f32_e32 v225, v173
	v_cvt_pk_bf16_f32 v172, v219, v221
	v_cvt_pk_bf16_f32 v173, v217, v218
	v_cvt_pk_bf16_f32 v174, v167, v169
	v_permlane32_swap_b32_e32 v175, v177
	s_waitcnt lgkmcnt(5)
	v_mfma_f32_32x32x16_bf16 v[80:95], v[64:67], v[136:139], 0
	s_waitcnt lgkmcnt(4)
	v_mfma_f32_32x32x16_bf16 v[80:95], v[244:247], v[132:135], v[80:95]
	s_waitcnt lgkmcnt(3)
	v_mfma_f32_32x32x16_bf16 v[80:95], v[226:229], v[128:131], v[80:95]
	ds_read_b128 v[244:247], v253 offset:16384
	s_waitcnt lgkmcnt(3)
	v_mfma_f32_32x32x16_bf16 v[64:79], v[68:71], v[136:139], 0
	ds_read_b128 v[226:229], v144 offset:16384
	s_waitcnt lgkmcnt(3)
	v_mfma_f32_32x32x16_bf16 v[64:79], v[248:251], v[132:135], v[64:79]
	s_waitcnt lgkmcnt(2)
	v_mfma_f32_32x32x16_bf16 v[64:79], v[230:233], v[128:131], v[64:79]
	ds_read_b128 v[248:251], v253 offset:24576
	v_add_u32_e32 v253, s63, v206
	ds_read_b128 v[230:233], v144 offset:24576
	v_add_u32_e32 v144, s63, v207
	s_waitcnt lgkmcnt(3)
	v_mfma_f32_32x32x16_bf16 v[80:95], v[244:247], v[124:127], v[80:95]
	s_waitcnt lgkmcnt(2)
	v_mfma_f32_32x32x16_bf16 v[80:95], v[226:229], v[120:123], v[80:95]
	ds_read_b128 v[244:247], v243 offset:16384
	ds_read_b128 v[226:229], v252 offset:16384
	s_waitcnt lgkmcnt(3)
	v_mfma_f32_32x32x16_bf16 v[64:79], v[248:251], v[124:127], v[64:79]
	s_waitcnt lgkmcnt(2)
	v_mfma_f32_32x32x16_bf16 v[64:79], v[230:233], v[120:123], v[64:79]
	ds_read_b128 v[248:251], v243 offset:24576
	v_add_u32_e32 v243, s63, v208
	ds_read_b128 v[230:233], v252 offset:24576
	v_add_u32_e32 v252, s63, v209
	s_waitcnt lgkmcnt(3)
	v_mfma_f32_32x32x16_bf16 v[80:95], v[244:247], v[112:115], v[80:95]
	s_waitcnt lgkmcnt(2)
	v_mfma_f32_32x32x16_bf16 v[80:95], v[226:229], v[108:111], v[80:95]
	ds_read_b128 v[244:247], v253 offset:16384
	ds_read_b128 v[226:229], v144 offset:32768
	s_waitcnt lgkmcnt(3)
	v_mfma_f32_32x32x16_bf16 v[64:79], v[248:251], v[112:115], v[64:79]
	s_waitcnt lgkmcnt(2)
	v_mfma_f32_32x32x16_bf16 v[64:79], v[230:233], v[108:111], v[64:79]
	ds_read_b128 v[248:251], v253 offset:24576
	v_add_u32_e32 v253, s63, v210
	ds_read_b128 v[230:233], v144 offset:36864
	v_exp_f32_e32 v144, v184
	v_exp_f32_e32 v184, v176
	v_cvt_pk_bf16_f32 v176, v163, v165
	s_waitcnt lgkmcnt(3)
	v_mfma_f32_32x32x16_bf16 v[80:95], v[244:247], v[100:103], v[80:95]
	s_waitcnt lgkmcnt(2)
	v_mfma_f32_32x32x16_bf16 v[80:95], v[226:229], v[104:107], v[80:95]
	ds_read_b128 v[244:247], v243 offset:32768
	v_permlane32_swap_b32_e32 v174, v176
	ds_read_b128 v[226:229], v252 offset:32768
	s_waitcnt lgkmcnt(3)
	v_mfma_f32_32x32x16_bf16 v[64:79], v[248:251], v[100:103], v[64:79]
	s_waitcnt lgkmcnt(2)
	v_mfma_f32_32x32x16_bf16 v[64:79], v[230:233], v[104:107], v[64:79]
	ds_read_b128 v[248:251], v243 offset:36864
	v_add_u32_e32 v243, s1, v147
	ds_read_b128 v[230:233], v252 offset:36864
	s_waitcnt lgkmcnt(3)
	v_mfma_f32_32x32x16_bf16 v[80:95], v[244:247], v[140:143], v[80:95]
	s_waitcnt lgkmcnt(2)
	v_mfma_f32_32x32x16_bf16 v[80:95], v[226:229], v[96:99], v[80:95]
	ds_read_b128 v[244:247], v253 offset:32768
	v_exp_f32_e32 v226, v170
	v_add_f32_e32 v170, v224, v222
	v_exp_f32_e32 v227, v171
	v_add_f32_e32 v170, v220, v170
	v_cvt_pk_bf16_f32 v171, v220, v223
	v_add_f32_e32 v170, v223, v170
	s_waitcnt lgkmcnt(2)
	v_mfma_f32_32x32x16_bf16 v[64:79], v[248:251], v[140:143], v[64:79]
	v_add_f32_e32 v170, v219, v170
	v_permlane32_swap_b32_e32 v171, v173
	v_add_f32_e32 v170, v221, v170
	ds_read_b64_tr_b16 v[220:221], v243 offset:0x3000
	v_add_f32_e32 v170, v217, v170
	s_waitcnt lgkmcnt(2)
	v_mfma_f32_32x32x16_bf16 v[64:79], v[230:233], v[96:99], v[64:79]
	v_add_f32_e32 v170, v218, v170
	ds_read_b64_tr_b16 v[218:219], v243 offset:0x2800
	v_add_f32_e32 v170, v167, v170
	v_cvt_pk_bf16_f32 v167, v186, v215
	v_add_f32_e32 v170, v169, v170
	v_cvt_pk_bf16_f32 v169, v226, v227
	v_add_f32_e32 v170, v166, v170
	v_cvt_pk_bf16_f32 v166, v184, v185
	v_add_f32_e32 v170, v168, v170
	v_cvt_pk_bf16_f32 v168, v216, v225
	v_add_f32_e32 v170, v163, v170
	v_cvt_pk_bf16_f32 v163, v182, v183
	v_add_f32_e32 v170, v165, v170
	v_cvt_pk_bf16_f32 v165, v178, v179
	v_add_f32_e32 v170, v162, v170
	v_cvt_pk_bf16_f32 v162, v144, v160
	v_add_f32_e32 v170, v164, v170
	v_cvt_pk_bf16_f32 v164, v180, v181
	v_add_f32_e32 v170, v144, v170
	v_permlane32_swap_b32_e32 v163, v165
	v_add_f32_e32 v170, v160, v170
	v_permlane32_swap_b32_e32 v162, v164
	v_add_f32_e32 v170, v182, v170
	ds_read_b128 v[230:233], v253 offset:36864
	v_add_f32_e32 v170, v183, v170
	ds_read_b64_tr_b16 v[182:183], v243 offset:0x1000
	v_add_f32_e32 v170, v180, v170
	v_permlane32_swap_b32_e32 v166, v168
	v_add_f32_e32 v170, v181, v170
	ds_read_b64_tr_b16 v[180:181], v243 offset:0x800
	v_add_f32_e32 v170, v178, v170
	v_permlane32_swap_b32_e32 v167, v169
	v_add_f32_e32 v170, v179, v170
	ds_read_b64_tr_b16 v[178:179], v243 offset:0
	v_add_f32_e32 v170, v184, v170
	v_add_f32_e32 v170, v185, v170
	ds_read_b64_tr_b16 v[184:185], v243 offset:0x1800
	v_add_f32_e32 v170, v186, v170
	v_add_f32_e32 v170, v215, v170
	s_waitcnt lgkmcnt(7)
; #define SBAR() __builtin_amdgcn_sched_barrier(0)
; DI void partialSM(f32x16& p0, f32x16& p1, float& m_reg, float& mn, float& alpha, const float SCALE) {
;   const float C = SCALE * 1.4426950408889634f;
;   float pmax = p0[0];
; #pragma unroll
;   for (int r = 1; r < 16; ++r) pmax = fmaxf(pmax, p0[r]);
; #pragma unroll
;   for (int r = 0; r < 16; ++r) pmax = fmaxf(pmax, p1[r]);
;   { auto rr = __builtin_amdgcn_permlane32_swap(__float_as_uint(pmax), __float_as_uint(pmax), false, false);
;     pmax = fmaxf(__uint_as_float(rr[0]), __uint_as_float(rr[1])); }
;   if (__builtin_expect(__all(pmax - m_reg <= THR / SCALE), 1)) { mn = m_reg; alpha = 1.f; }
;   else { mn = fmaxf(m_reg, pmax); alpha = __builtin_amdgcn_exp2f((m_reg - mn) * C); m_reg = mn; }
; template <int D0, bool SPLIT> DI void pv_one(f32x16& od, int vb, bf16x8 pa0, bf16x8 pa1, bf16x8 pa2, bf16x8 pa3) {
;     ...
;   const s16x4 l0 = tr_read<v_rd_off(D0, 0, 0)>(vb), h0 = tr_read<v_rd_off(D0, 0, 1)>(vb), l1 = tr_read<v_rd_off(D0, 1, 0)>(vb), h1 = tr_read<v_rd_off(D0, 1, 1)>(vb);
;   const s16x4 l2 = tr_read<v_rd_off(D0, 2, 0)>(vb), h2 = tr_read<v_rd_off(D0, 2, 1)>(vb), l3 = tr_read<v_rd_off(D0, 3, 0)>(vb), h3 = tr_read<v_rd_off(D0, 3, 1)>(vb);
;   asm volatile("s_waitcnt lgkmcnt(0)" ::: "memory"); SBAR();
;   od = __builtin_amdgcn_mfma_f32_32x32x16_bf16(PKV(l0, h0), pa0, od, 0, 0, 0);
;   od = __builtin_amdgcn_mfma_f32_32x32x16_bf16(PKV(l1, h1), pa1, od, 0, 0, 0);
;   od = __builtin_amdgcn_mfma_f32_32x32x16_bf16(PKV(l2, h2), pa2, od, 0, 0, 0);
;   od = __builtin_amdgcn_mfma_f32_32x32x16_bf16(PKV(l3, h3), pa3, od, 0, 0, 0);
	v_mfma_f32_32x32x16_bf16 v[80:95], v[244:247], v[116:119], v[80:95]
	v_add_f32_e32 v170, v216, v170
	ds_read_b64_tr_b16 v[216:217], v243 offset:0x2000
	v_add_f32_e32 v170, v225, v170
	v_add_f32_e32 v170, v226, v170
	v_add_f32_e32 v213, v227, v170
	v_cvt_pk_bf16_f32 v170, v222, v224
	ds_read_b64_tr_b16 v[222:223], v243 offset:0x3800
	ds_read_b64_tr_b16 v[224:225], v243 offset:0x3200
	ds_read_b64_tr_b16 v[226:227], v243 offset:0x3a00
	v_permlane32_swap_b32_e32 v170, v172
	v_mov_b32_e32 v214, v213
	s_waitcnt lgkmcnt(8)
	v_mfma_f32_32x32x16_bf16 v[64:79], v[230:233], v[116:119], v[64:79]
	v_max_f32_e32 v252, v80, v81
	v_permlane32_swap_b32_e32 v213, v214
	v_max3_f32 v252, v252, v82, v83
	v_max3_f32 v252, v252, v84, v85
	v_max3_f32 v252, v252, v86, v87
	v_max3_f32 v252, v252, v88, v89
	s_waitcnt lgkmcnt(5)
	v_mfma_f32_32x32x16_bf16 v[16:31], v[178:181], v[170:173], v[16:31]
	v_max3_f32 v252, v252, v90, v91
	v_max3_f32 v252, v252, v92, v93
	v_max3_f32 v252, v252, v94, v95
	s_waitcnt lgkmcnt(4)
	v_mfma_f32_32x32x16_bf16 v[16:31], v[182:185], v[174:177], v[16:31]
	ds_read_b64_tr_b16 v[178:179], v243 offset:0x200
	ds_read_b64_tr_b16 v[180:181], v243 offset:0xa00
	v_max3_f32 v252, v252, v64, v65
	v_max3_f32 v252, v252, v66, v67
	s_waitcnt lgkmcnt(5)
	v_mfma_f32_32x32x16_bf16 v[16:31], v[216:219], v[162:165], v[16:31]
	ds_read_b64_tr_b16 v[182:183], v243 offset:0x1200
	ds_read_b64_tr_b16 v[184:185], v243 offset:0x1a00
	v_max3_f32 v252, v252, v68, v69
	v_max3_f32 v252, v252, v70, v71
	s_waitcnt lgkmcnt(6)
	v_mfma_f32_32x32x16_bf16 v[16:31], v[220:223], v[166:169], v[16:31]
	ds_read_b64_tr_b16 v[216:217], v243 offset:0x2200
	ds_read_b64_tr_b16 v[218:219], v243 offset:0x2a00
	v_max3_f32 v252, v252, v72, v73
	v_max3_f32 v252, v252, v74, v75
	ds_read_b64_tr_b16 v[220:221], v243 offset:0x3400
	ds_read_b64_tr_b16 v[222:223], v243 offset:0x3c00
	v_max3_f32 v252, v252, v76, v77
	v_max3_f32 v252, v252, v78, v79
	v_mov_b32_e32 v160, v252
	s_waitcnt lgkmcnt(6)
	v_mfma_f32_32x32x16_bf16 v[48:63], v[178:181], v[170:173], v[48:63]
	s_waitcnt lgkmcnt(4)
	v_mfma_f32_32x32x16_bf16 v[48:63], v[182:185], v[174:177], v[48:63]
	ds_read_b64_tr_b16 v[178:179], v243 offset:0x400
	ds_read_b64_tr_b16 v[180:181], v243 offset:0xc00
	v_permlane32_swap_b32_e32 v252, v160
	v_max_f32_e32 v252, v252, v160
	s_waitcnt lgkmcnt(4)
	v_mfma_f32_32x32x16_bf16 v[48:63], v[216:219], v[162:165], v[48:63]
	ds_read_b64_tr_b16 v[182:183], v243 offset:0x1400
	ds_read_b64_tr_b16 v[184:185], v243 offset:0x1c00
	v_max_f32_e32 v160, v212, v252
	v_sub_f32_e32 v144, v212, v160
	v_mfma_f32_32x32x16_bf16 v[48:63], v[224:227], v[166:169], v[48:63]
	ds_read_b64_tr_b16 v[216:217], v243 offset:0x2400
	ds_read_b64_tr_b16 v[218:219], v243 offset:0x2c00
	v_mul_f32_e32 v144, 0x3dd53b94, v144
	v_exp_f32_e32 v144, v144
	ds_read_b64_tr_b16 v[224:225], v243 offset:0x3600
	ds_read_b64_tr_b16 v[226:227], v243 offset:0x3e00
	s_waitcnt lgkmcnt(6)
	v_mfma_f32_32x32x16_bf16 v[32:47], v[178:181], v[170:173], v[32:47]
	s_waitcnt lgkmcnt(4)
	v_mfma_f32_32x32x16_bf16 v[32:47], v[182:185], v[174:177], v[32:47]
	ds_read_b64_tr_b16 v[178:179], v243 offset:0x600
	ds_read_b64_tr_b16 v[180:181], v243 offset:0xe00
	s_waitcnt lgkmcnt(4)
	v_mfma_f32_32x32x16_bf16 v[32:47], v[216:219], v[162:165], v[32:47]
	ds_read_b64_tr_b16 v[182:183], v243 offset:0x1600
	ds_read_b64_tr_b16 v[184:185], v243 offset:0x1e00
	v_mfma_f32_32x32x16_bf16 v[32:47], v[220:223], v[166:169], v[32:47]
	ds_read_b64_tr_b16 v[216:217], v243 offset:0x2600
	ds_read_b64_tr_b16 v[218:219], v243 offset:0x2e00
	s_waitcnt lgkmcnt(4)
	v_mfma_f32_32x32x16_bf16 v[0:15], v[178:181], v[170:173], v[0:15]
	s_waitcnt lgkmcnt(2)
	v_mfma_f32_32x32x16_bf16 v[0:15], v[182:185], v[174:177], v[0:15]
	s_waitcnt lgkmcnt(0)
	v_mfma_f32_32x32x16_bf16 v[0:15], v[216:219], v[162:165], v[0:15]
	v_mfma_f32_32x32x16_bf16 v[0:15], v[224:227], v[166:169], v[0:15]
	v_sub_f32_e32 v162, v252, v212
	v_cmp_ge_f32_e32 vcc, s91, v162
	s_cmp_eq_u64 vcc, exec
	s_cselect_b64 s[2:3], -1, 0
	v_cndmask_b32_e64 v144, v144, 1.0, s[2:3]
	s_cbranch_scc1 .LBB0_930
	v_pk_mul_f32 v[30:31], v[30:31], v[144:145] op_sel_hi:[1,0]
	v_pk_mul_f32 v[28:29], v[28:29], v[144:145] op_sel_hi:[1,0]
	v_pk_mul_f32 v[26:27], v[26:27], v[144:145] op_sel_hi:[1,0]
	v_pk_mul_f32 v[24:25], v[24:25], v[144:145] op_sel_hi:[1,0]
	v_pk_mul_f32 v[22:23], v[22:23], v[144:145] op_sel_hi:[1,0]
	v_pk_mul_f32 v[20:21], v[20:21], v[144:145] op_sel_hi:[1,0]
	v_pk_mul_f32 v[18:19], v[18:19], v[144:145] op_sel_hi:[1,0]
	v_pk_mul_f32 v[16:17], v[16:17], v[144:145] op_sel_hi:[1,0]
	v_pk_mul_f32 v[62:63], v[62:63], v[144:145] op_sel_hi:[1,0]
	v_pk_mul_f32 v[60:61], v[60:61], v[144:145] op_sel_hi:[1,0]
	v_pk_mul_f32 v[58:59], v[58:59], v[144:145] op_sel_hi:[1,0]
	v_pk_mul_f32 v[56:57], v[56:57], v[144:145] op_sel_hi:[1,0]
	v_pk_mul_f32 v[54:55], v[54:55], v[144:145] op_sel_hi:[1,0]
	v_pk_mul_f32 v[52:53], v[52:53], v[144:145] op_sel_hi:[1,0]
	v_pk_mul_f32 v[50:51], v[50:51], v[144:145] op_sel_hi:[1,0]
	v_pk_mul_f32 v[48:49], v[48:49], v[144:145] op_sel_hi:[1,0]
	v_pk_mul_f32 v[46:47], v[46:47], v[144:145] op_sel_hi:[1,0]
	v_pk_mul_f32 v[44:45], v[44:45], v[144:145] op_sel_hi:[1,0]
	v_pk_mul_f32 v[42:43], v[42:43], v[144:145] op_sel_hi:[1,0]
	v_pk_mul_f32 v[40:41], v[40:41], v[144:145] op_sel_hi:[1,0]
	v_pk_mul_f32 v[38:39], v[38:39], v[144:145] op_sel_hi:[1,0]
	v_pk_mul_f32 v[36:37], v[36:37], v[144:145] op_sel_hi:[1,0]
	v_pk_mul_f32 v[34:35], v[34:35], v[144:145] op_sel_hi:[1,0]
	v_pk_mul_f32 v[32:33], v[32:33], v[144:145] op_sel_hi:[1,0]
	v_pk_mul_f32 v[14:15], v[14:15], v[144:145] op_sel_hi:[1,0]
	v_pk_mul_f32 v[12:13], v[12:13], v[144:145] op_sel_hi:[1,0]
	v_pk_mul_f32 v[10:11], v[10:11], v[144:145] op_sel_hi:[1,0]
	v_pk_mul_f32 v[8:9], v[8:9], v[144:145] op_sel_hi:[1,0]
	v_pk_mul_f32 v[6:7], v[6:7], v[144:145] op_sel_hi:[1,0]
	v_pk_mul_f32 v[4:5], v[4:5], v[144:145] op_sel_hi:[1,0]
	v_pk_mul_f32 v[2:3], v[2:3], v[144:145] op_sel_hi:[1,0]
	v_pk_mul_f32 v[0:1], v[0:1], v[144:145] op_sel_hi:[1,0]
; DI void partialSM(f32x16& p0, f32x16& p1, float& m_reg, float& mn, float& alpha, const float SCALE) {
;     ...
;   float mnC = -mn * C;
; #pragma unroll
;   for (int r = 0; r < 16; ++r) p0[r] = fmaf(p0[r], C, mnC);
; #pragma unroll
;   for (int r = 0; r < 16; ++r) p1[r] = fmaf(p1[r], C, mnC);
; #pragma unroll
;   for (int r = 0; r < 16; ++r) p0[r] = __builtin_amdgcn_exp2f(p0[r]);
.LBB0_930:
	v_cndmask_b32_e64 v170, v160, v212, s[2:3]
	s_waitcnt vmcnt(0) lgkmcnt(0)
	v_add_u32_e32 v243, s62, v191
	v_mul_f32_e32 v160, 0xbdd53b94, v170
	s_barrier
	v_fmamk_f32 v80, v80, 0x3dd53b94, v160
	v_fmamk_f32 v81, v81, 0x3dd53b94, v160
	v_fmamk_f32 v82, v82, 0x3dd53b94, v160
	v_fmamk_f32 v83, v83, 0x3dd53b94, v160
	v_fmamk_f32 v183, v68, 0x3dd53b94, v160
	v_add_u32_e32 v68, s62, v188
	v_exp_f32_e32 v219, v80
	v_exp_f32_e32 v220, v81
	v_exp_f32_e32 v221, v82
	v_exp_f32_e32 v222, v83
	ds_read_b128 v[80:83], v68 offset:24576
	ds_read_b128 v[176:179], v243 offset:24576
	v_fmamk_f32 v84, v84, 0x3dd53b94, v160
	v_fmamk_f32 v85, v85, 0x3dd53b94, v160
	v_fmamk_f32 v86, v86, 0x3dd53b94, v160
	v_fmamk_f32 v87, v87, 0x3dd53b94, v160
	v_fmamk_f32 v88, v88, 0x3dd53b94, v160
	v_fmamk_f32 v89, v89, 0x3dd53b94, v160
	v_fmamk_f32 v90, v90, 0x3dd53b94, v160
	v_fmamk_f32 v91, v91, 0x3dd53b94, v160
	v_fmamk_f32 v92, v92, 0x3dd53b94, v160
	v_fmamk_f32 v93, v93, 0x3dd53b94, v160
	v_fmamk_f32 v94, v94, 0x3dd53b94, v160
	v_fmamk_f32 v95, v95, 0x3dd53b94, v160
	v_exp_f32_e32 v223, v84
	v_exp_f32_e32 v224, v85
	v_exp_f32_e32 v225, v86
	v_exp_f32_e32 v226, v87
	v_exp_f32_e32 v227, v88
	v_exp_f32_e32 v228, v89
	v_exp_f32_e32 v229, v90
	v_exp_f32_e32 v230, v91
	v_exp_f32_e32 v231, v92
	v_exp_f32_e32 v232, v93
	v_exp_f32_e32 v233, v94
	v_exp_f32_e32 v234, v95
	v_add_u32_e32 v252, s62, v194
	v_fmamk_f32 v171, v64, 0x3dd53b94, v160
	v_fmamk_f32 v180, v65, 0x3dd53b94, v160
	v_fmamk_f32 v181, v66, 0x3dd53b94, v160
	v_fmamk_f32 v182, v67, 0x3dd53b94, v160
	ds_read_b128 v[64:67], v68 offset:16384
	v_add_u32_e32 v253, s62, v197
	ds_read_b128 v[244:247], v243 offset:16384
	v_fmamk_f32 v184, v69, 0x3dd53b94, v160
	v_fmamk_f32 v185, v70, 0x3dd53b94, v160
	v_fmamk_f32 v186, v71, 0x3dd53b94, v160
	v_fmamk_f32 v212, v72, 0x3dd53b94, v160
	v_fmamk_f32 v215, v73, 0x3dd53b94, v160
	v_fmamk_f32 v216, v74, 0x3dd53b94, v160
	v_fmamk_f32 v217, v75, 0x3dd53b94, v160
	v_fmamk_f32 v218, v76, 0x3dd53b94, v160
	v_fmamk_f32 v235, v77, 0x3dd53b94, v160
	v_fmamk_f32 v236, v78, 0x3dd53b94, v160
	v_fmac_f32_e32 v160, 0x3dd53b94, v79
	v_add_u32_e32 v243, s62, v203
	ds_read_b128 v[248:251], v252 offset:16384
	ds_read_b128 v[172:175], v253 offset:16384
	v_exp_f32_e32 v171, v171
	s_waitcnt lgkmcnt(5)
	v_mfma_f32_32x32x16_bf16 v[80:95], v[80:83], v[136:139], 0
	v_exp_f32_e32 v180, v180
	v_exp_f32_e32 v181, v181
	v_exp_f32_e32 v182, v182
	s_waitcnt lgkmcnt(4)
	v_mfma_f32_32x32x16_bf16 v[80:95], v[176:179], v[132:135], v[80:95]
	v_exp_f32_e32 v183, v183
	v_exp_f32_e32 v184, v184
	v_exp_f32_e32 v185, v185
	ds_read_b128 v[176:179], v252 offset:24576
	v_add_u32_e32 v252, s62, v205
	v_exp_f32_e32 v186, v186
	v_exp_f32_e32 v212, v212
	v_exp_f32_e32 v237, v215
	v_exp_f32_e32 v238, v216
	v_exp_f32_e32 v217, v217
	v_exp_f32_e32 v239, v218
	v_exp_f32_e32 v235, v235
	v_exp_f32_e32 v236, v236
	v_exp_f32_e32 v160, v160
	v_cvt_pk_bf16_f32 v218, v212, v237
	s_lshl_b32 s30, s101, 11
	v_lshl_add_u64 v[162:163], v[154:155], 0, s[38:39]
	s_add_i32 s30, s30, s1
	v_lshl_add_u64 v[164:165], v[156:157], 0, s[40:41]
	s_mov_b32 m0, s30
	s_add_i32 s31, s30, 0x4000
	v_lshl_add_u64 v[166:167], v[154:155], 0, s[42:43]
	global_load_lds_dwordx4 v[162:163], off
	s_waitcnt lgkmcnt(4)
	v_mfma_f32_32x32x16_bf16 v[64:79], v[64:67], v[136:139], 0
	s_mov_b32 m0, s31
	s_addk_i32 s30, 0x400
	v_lshl_add_u64 v[168:169], v[158:159], 0, s[40:41]
	s_addk_i32 s31, 0x400
	global_load_lds_dwordx4 v[164:165], off
	s_mov_b32 m0, s30
	s_waitcnt lgkmcnt(3)
	v_mfma_f32_32x32x16_bf16 v[64:79], v[244:247], v[132:135], v[64:79]
	s_lshl_b32 s30, s101, 10
	global_load_lds_dwordx4 v[166:167], off
	s_add_i32 s30, s30, s1
	s_mov_b32 m0, s31
	v_lshl_add_u64 v[162:163], v[152:153], 0, s[44:45]
	s_add_i32 s30, s30, 0x8000
	s_waitcnt lgkmcnt(2)
	v_mfma_f32_32x32x16_bf16 v[64:79], v[248:251], v[128:131], v[64:79]
	global_load_lds_dwordx4 v[168:169], off
	s_mov_b32 m0, s30
	s_waitcnt lgkmcnt(1)
	v_mfma_f32_32x32x16_bf16 v[64:79], v[172:175], v[124:127], v[64:79]
	ds_read_b128 v[248:251], v243 offset:16384
	global_load_lds_dwordx4 v[162:163], off
	ds_read_b128 v[172:175], v252 offset:16384
	s_waitcnt lgkmcnt(2)
	v_mfma_f32_32x32x16_bf16 v[80:95], v[176:179], v[128:131], v[80:95]
	ds_read_b128 v[176:179], v253 offset:24576
	v_add_u32_e32 v253, s62, v206
	s_waitcnt lgkmcnt(0)
	v_mfma_f32_32x32x16_bf16 v[80:95], v[176:179], v[124:127], v[80:95]
	v_add_u32_e32 v176, s62, v200
	ds_read_b128 v[244:247], v176 offset:16384
	ds_read_b128 v[176:179], v176 offset:24576
	s_waitcnt lgkmcnt(1)
	v_mfma_f32_32x32x16_bf16 v[64:79], v[244:247], v[120:123], v[64:79]
	s_waitcnt lgkmcnt(0)
	v_mfma_f32_32x32x16_bf16 v[80:95], v[176:179], v[120:123], v[80:95]
	ds_read_b128 v[244:247], v253 offset:16384
	v_mfma_f32_32x32x16_bf16 v[64:79], v[248:251], v[112:115], v[64:79]
	ds_read_b128 v[176:179], v243 offset:24576
	v_add_u32_e32 v243, s62, v208
	v_mfma_f32_32x32x16_bf16 v[64:79], v[172:175], v[108:111], v[64:79]
	ds_read_b128 v[172:175], v243 offset:32768
	s_waitcnt lgkmcnt(2)
	v_mfma_f32_32x32x16_bf16 v[64:79], v[244:247], v[100:103], v[64:79]
	s_waitcnt lgkmcnt(1)
	v_mfma_f32_32x32x16_bf16 v[80:95], v[176:179], v[112:115], v[80:95]
	ds_read_b128 v[176:179], v252 offset:24576
	v_add_u32_e32 v252, s62, v209
	ds_read_b128 v[244:247], v252 offset:32768
	s_waitcnt lgkmcnt(1)
	v_mfma_f32_32x32x16_bf16 v[80:95], v[176:179], v[108:111], v[80:95]
	ds_read_b128 v[176:179], v253 offset:24576
	v_add_u32_e32 v253, s62, v210
	s_waitcnt lgkmcnt(0)
	v_mfma_f32_32x32x16_bf16 v[80:95], v[176:179], v[100:103], v[80:95]
	v_add_u32_e32 v176, s62, v207
	ds_read_b128 v[248:251], v176 offset:32768
	ds_read_b128 v[176:179], v176 offset:36864
	s_waitcnt lgkmcnt(1)
; DI void partialSM(f32x16& p0, f32x16& p1, float& m_reg, float& mn, float& alpha, const float SCALE) {
;   const float C = SCALE * 1.4426950408889634f;
;   float pmax = p0[0];
; #pragma unroll
;   for (int r = 1; r < 16; ++r) pmax = fmaxf(pmax, p0[r]);
; #pragma unroll
;   for (int r = 0; r < 16; ++r) pmax = fmaxf(pmax, p1[r]);
;   { auto rr = __builtin_amdgcn_permlane32_swap(__float_as_uint(pmax), __float_as_uint(pmax), false, false);
;     pmax = fmaxf(__uint_as_float(rr[0]), __uint_as_float(rr[1])); }
;   if (__builtin_expect(__all(pmax - m_reg <= THR / SCALE), 1)) { mn = m_reg; alpha = 1.f; }
;   else { mn = fmaxf(m_reg, pmax); alpha = __builtin_amdgcn_exp2f((m_reg - mn) * C); m_reg = mn; }
; DI void finishSM(f32x16& p0, f32x16& p1, float alpha, float& l_reg, bf16x8& pa0, bf16x8& pa1, bf16x8& pa2, bf16x8& pa3) {
; #pragma unroll
;   for (int r = 0; r < 16; ++r) p1[r] = __builtin_amdgcn_exp2f(p1[r]);
;   float ps = 0;
; #pragma unroll
;   for (int r = 0; r < 16; ++r) ps += p0[r];
; #pragma unroll
;   for (int r = 0; r < 16; ++r) ps += p1[r];
;   { auto rr = __builtin_amdgcn_permlane32_swap(__float_as_uint(ps), __float_as_uint(ps), false, false);
;     ps = __uint_as_float(rr[0]) + __uint_as_float(rr[1]); }
;   l_reg = l_reg * alpha + ps;
;   PK4(p0, 0, pa0); PK4(p0, 8, pa1); PK4(p1, 0, pa2); PK4(p1, 8, pa3);
; }
	v_mfma_f32_32x32x16_bf16 v[64:79], v[248:251], v[104:107], v[64:79]
	s_waitcnt lgkmcnt(0)
	v_mfma_f32_32x32x16_bf16 v[80:95], v[176:179], v[104:107], v[80:95]
	ds_read_b128 v[248:251], v253 offset:32768
	v_mfma_f32_32x32x16_bf16 v[64:79], v[172:175], v[140:143], v[64:79]
	ds_read_b128 v[176:179], v243 offset:36864
	v_mfma_f32_32x32x16_bf16 v[64:79], v[244:247], v[96:99], v[64:79]
	v_add_f32_e32 v172, v220, v219
	v_cvt_pk_bf16_f32 v173, v221, v222
	v_add_f32_e32 v172, v221, v172
	v_cvt_pk_bf16_f32 v221, v236, v160
	v_add_f32_e32 v172, v222, v172
	v_cvt_pk_bf16_f32 v174, v223, v224
	v_add_f32_e32 v172, v223, v172
	v_cvt_pk_bf16_f32 v175, v225, v226
	v_add_f32_e32 v172, v224, v172
	v_add_f32_e32 v172, v225, v172
	v_permlane32_swap_b32_e32 v173, v175
	v_add_f32_e32 v172, v226, v172
	v_add_f32_e32 v172, v227, v172
	v_add_f32_e32 v172, v228, v172
	v_add_f32_e32 v172, v229, v172
	v_add_f32_e32 v172, v230, v172
	v_add_f32_e32 v172, v231, v172
	v_add_f32_e32 v172, v232, v172
	v_add_f32_e32 v172, v233, v172
	v_add_f32_e32 v172, v234, v172
	v_add_f32_e32 v172, v171, v172
	v_add_f32_e32 v172, v180, v172
	v_cvt_pk_bf16_f32 v180, v171, v180
	v_add_f32_e32 v172, v181, v172
	v_cvt_pk_bf16_f32 v181, v181, v182
	v_add_f32_e32 v172, v182, v172
	v_cvt_pk_bf16_f32 v182, v183, v184
	v_add_f32_e32 v172, v183, v172
	v_cvt_pk_bf16_f32 v183, v185, v186
	v_add_f32_e32 v172, v184, v172
	v_permlane32_swap_b32_e32 v180, v182
	v_add_f32_e32 v172, v185, v172
	v_permlane32_swap_b32_e32 v181, v183
	v_add_f32_e32 v172, v186, v172
	v_add_f32_e32 v172, v212, v172
	v_add_f32_e32 v172, v237, v172
	s_waitcnt lgkmcnt(1)
	v_mfma_f32_32x32x16_bf16 v[64:79], v[248:251], v[116:119], v[64:79]
	v_add_f32_e32 v172, v238, v172
	v_add_f32_e32 v172, v217, v172
	v_add_f32_e32 v172, v239, v172
	s_waitcnt lgkmcnt(0)
	v_mfma_f32_32x32x16_bf16 v[80:95], v[176:179], v[140:143], v[80:95]
	v_add_f32_e32 v172, v235, v172
	v_add_f32_e32 v172, v236, v172
	v_add_f32_e32 v215, v160, v172
	v_add_u32_e32 v160, s63, v147
	ds_read_b128 v[176:179], v252 offset:36864
	ds_read_b64_tr_b16 v[222:223], v160 offset:0
	ds_read_b64_tr_b16 v[224:225], v160 offset:0x800
	v_cvt_pk_bf16_f32 v172, v219, v220
	v_cvt_pk_bf16_f32 v219, v238, v217
	v_cvt_pk_bf16_f32 v220, v239, v235
	ds_read_b64_tr_b16 v[236:237], v160 offset:0x3800
	v_permlane32_swap_b32_e32 v172, v174
	ds_read_b64_tr_b16 v[238:239], v160 offset:0x3200
	ds_read_b64_tr_b16 v[240:241], v160 offset:0x3a00
	v_permlane32_swap_b32_e32 v218, v220
	v_permlane32_swap_b32_e32 v219, v221
	v_mov_b32_e32 v216, v215
	s_waitcnt lgkmcnt(5)
	v_mfma_f32_32x32x16_bf16 v[80:95], v[176:179], v[96:99], v[80:95]
	s_waitcnt lgkmcnt(3)
	v_mfma_f32_32x32x16_bf16 v[16:31], v[222:225], v[172:175], v[16:31]
	ds_read_b128 v[176:179], v253 offset:36864
	v_permlane32_swap_b32_e32 v215, v216
	ds_read_b64_tr_b16 v[222:223], v160 offset:0x200
	ds_read_b64_tr_b16 v[224:225], v160 offset:0xa00
	s_waitcnt lgkmcnt(2)
	v_mfma_f32_32x32x16_bf16 v[80:95], v[176:179], v[116:119], v[80:95]
	s_waitcnt lgkmcnt(0)
	v_mfma_f32_32x32x16_bf16 v[48:63], v[222:225], v[172:175], v[48:63]
	v_cvt_pk_bf16_f32 v176, v227, v228
	v_cvt_pk_bf16_f32 v177, v229, v230
	ds_read_b64_tr_b16 v[226:227], v160 offset:0x1000
	ds_read_b64_tr_b16 v[228:229], v160 offset:0x1800
	v_cvt_pk_bf16_f32 v178, v231, v232
	v_cvt_pk_bf16_f32 v179, v233, v234
	ds_read_b64_tr_b16 v[230:231], v160 offset:0x2000
	ds_read_b64_tr_b16 v[232:233], v160 offset:0x2800
	v_permlane32_swap_b32_e32 v176, v178
	v_permlane32_swap_b32_e32 v177, v179
	ds_read_b64_tr_b16 v[222:223], v160 offset:0x400
	ds_read_b64_tr_b16 v[224:225], v160 offset:0xc00
	ds_read_b64_tr_b16 v[234:235], v160 offset:0x3000
	s_waitcnt lgkmcnt(5)
	v_mfma_f32_32x32x16_bf16 v[16:31], v[226:229], v[176:179], v[16:31]
	s_waitcnt lgkmcnt(3)
	v_mfma_f32_32x32x16_bf16 v[16:31], v[230:233], v[180:183], v[16:31]
	ds_read_b64_tr_b16 v[226:227], v160 offset:0x1200
	ds_read_b64_tr_b16 v[228:229], v160 offset:0x1a00
	s_waitcnt lgkmcnt(3)
	v_mfma_f32_32x32x16_bf16 v[32:47], v[222:225], v[172:175], v[32:47]
	ds_read_b64_tr_b16 v[230:231], v160 offset:0x2200
	ds_read_b64_tr_b16 v[232:233], v160 offset:0x2a00
	s_waitcnt lgkmcnt(4)
	v_mfma_f32_32x32x16_bf16 v[16:31], v[234:237], v[218:221], v[16:31]
	ds_read_b64_tr_b16 v[222:223], v160 offset:0x600
	ds_read_b64_tr_b16 v[224:225], v160 offset:0xe00
	ds_read_b64_tr_b16 v[234:235], v160 offset:0x3400
	ds_read_b64_tr_b16 v[236:237], v160 offset:0x3c00
	s_waitcnt lgkmcnt(6)
	v_mfma_f32_32x32x16_bf16 v[48:63], v[226:229], v[176:179], v[48:63]
	s_waitcnt lgkmcnt(4)
	v_mfma_f32_32x32x16_bf16 v[48:63], v[230:233], v[180:183], v[48:63]
	ds_read_b64_tr_b16 v[226:227], v160 offset:0x1400
	ds_read_b64_tr_b16 v[228:229], v160 offset:0x1c00
	v_mfma_f32_32x32x16_bf16 v[48:63], v[238:241], v[218:221], v[48:63]
	ds_read_b64_tr_b16 v[230:231], v160 offset:0x2400
	ds_read_b64_tr_b16 v[232:233], v160 offset:0x2c00
	s_waitcnt lgkmcnt(6)
	v_mfma_f32_32x32x16_bf16 v[0:15], v[222:225], v[172:175], v[0:15]
	ds_read_b64_tr_b16 v[238:239], v160 offset:0x3600
	ds_read_b64_tr_b16 v[240:241], v160 offset:0x3e00
	s_waitcnt lgkmcnt(4)
	v_mfma_f32_32x32x16_bf16 v[32:47], v[226:229], v[176:179], v[32:47]
	s_waitcnt lgkmcnt(2)
	v_mfma_f32_32x32x16_bf16 v[32:47], v[230:233], v[180:183], v[32:47]
	ds_read_b64_tr_b16 v[226:227], v160 offset:0x1600
	ds_read_b64_tr_b16 v[228:229], v160 offset:0x1e00
	v_mfma_f32_32x32x16_bf16 v[32:47], v[234:237], v[218:221], v[32:47]
	ds_read_b64_tr_b16 v[230:231], v160 offset:0x2600
	ds_read_b64_tr_b16 v[232:233], v160 offset:0x2e00
	v_max_f32_e32 v160, v64, v65
	v_max3_f32 v160, v160, v66, v67
	v_max3_f32 v160, v160, v68, v69
	v_max3_f32 v160, v160, v70, v71
	v_max3_f32 v160, v160, v72, v73
	v_max3_f32 v160, v160, v74, v75
	v_max3_f32 v160, v160, v76, v77
	v_max3_f32 v160, v160, v78, v79
	v_max3_f32 v160, v160, v80, v81
	v_max3_f32 v160, v160, v82, v83
	v_max3_f32 v160, v160, v84, v85
	v_max3_f32 v160, v160, v86, v87
	v_max3_f32 v160, v160, v88, v89
	v_max3_f32 v160, v160, v90, v91
	v_max3_f32 v160, v160, v92, v93
	v_max3_f32 v160, v160, v94, v95
	v_mov_b32_e32 v171, v160
	s_waitcnt lgkmcnt(2)
	v_mfma_f32_32x32x16_bf16 v[0:15], v[226:229], v[176:179], v[0:15]
	s_waitcnt lgkmcnt(0)
	v_mfma_f32_32x32x16_bf16 v[0:15], v[230:233], v[180:183], v[0:15]
	v_permlane32_swap_b32_e32 v160, v171
	v_max_f32_e32 v160, v160, v171
	v_max_f32_e32 v171, v170, v160
	v_sub_f32_e32 v172, v160, v170
	v_mfma_f32_32x32x16_bf16 v[0:15], v[238:241], v[218:221], v[0:15]
	v_sub_f32_e32 v160, v170, v171
	v_cmp_ge_f32_e32 vcc, s91, v172
	v_mul_f32_e32 v160, 0x3dd53b94, v160
	v_exp_f32_e32 v160, v160
	s_cmp_eq_u64 vcc, exec
	s_cselect_b64 s[2:3], -1, 0
	v_cndmask_b32_e64 v160, v160, 1.0, s[2:3]
	s_cbranch_scc1 .LBB0_932
; DI int v_rd_base(int lane) { return ((lane & 3) << 3) | (((lane >> 2) & 3) << 6) | (((lane >> 4) & 1) << 5) | (((lane >> 5) & 1) << 8); }
; #define RBAR() do { asm volatile("s_waitcnt vmcnt(0) lgkmcnt(0)" ::: "memory"); __builtin_amdgcn_s_barrier(); asm volatile("" ::: "memory"); } while (0)
; template <int NPE, int LDQ, int LDK, int VOFF, int LDO> ...
;     ...
;   f32x16 pA0, pA1, pB0, pB1; float mnA, mnB, alA, alB; bf16x8 pa0, pa1, pa2, pa3; const int NT = seq / KVBLK;
;   const int vlane = v_rd_base(lane);
;   RBAR();
;   ISSUE(2 * KVBLK, s_next);
;   qkt_r<NPE>(pA0, pA1, s_prev + R_K, s_prev + R_P, qr, r32, hi); partialSM(pA0, pA1, m_reg, mnA, alA, SCALE);
	v_pk_mul_f32 v[30:31], v[30:31], v[160:161] op_sel_hi:[1,0]
	v_pk_mul_f32 v[28:29], v[28:29], v[160:161] op_sel_hi:[1,0]
	v_pk_mul_f32 v[26:27], v[26:27], v[160:161] op_sel_hi:[1,0]
	v_pk_mul_f32 v[24:25], v[24:25], v[160:161] op_sel_hi:[1,0]
	v_pk_mul_f32 v[22:23], v[22:23], v[160:161] op_sel_hi:[1,0]
	v_pk_mul_f32 v[20:21], v[20:21], v[160:161] op_sel_hi:[1,0]
	v_pk_mul_f32 v[18:19], v[18:19], v[160:161] op_sel_hi:[1,0]
	v_pk_mul_f32 v[16:17], v[16:17], v[160:161] op_sel_hi:[1,0]
	v_pk_mul_f32 v[62:63], v[62:63], v[160:161] op_sel_hi:[1,0]
	v_pk_mul_f32 v[60:61], v[60:61], v[160:161] op_sel_hi:[1,0]
	v_pk_mul_f32 v[58:59], v[58:59], v[160:161] op_sel_hi:[1,0]
	v_pk_mul_f32 v[56:57], v[56:57], v[160:161] op_sel_hi:[1,0]
	v_pk_mul_f32 v[54:55], v[54:55], v[160:161] op_sel_hi:[1,0]
	v_pk_mul_f32 v[52:53], v[52:53], v[160:161] op_sel_hi:[1,0]
	v_pk_mul_f32 v[50:51], v[50:51], v[160:161] op_sel_hi:[1,0]
	v_pk_mul_f32 v[48:49], v[48:49], v[160:161] op_sel_hi:[1,0]
	v_pk_mul_f32 v[46:47], v[46:47], v[160:161] op_sel_hi:[1,0]
	v_pk_mul_f32 v[44:45], v[44:45], v[160:161] op_sel_hi:[1,0]
	v_pk_mul_f32 v[42:43], v[42:43], v[160:161] op_sel_hi:[1,0]
	v_pk_mul_f32 v[40:41], v[40:41], v[160:161] op_sel_hi:[1,0]
	v_pk_mul_f32 v[38:39], v[38:39], v[160:161] op_sel_hi:[1,0]
	v_pk_mul_f32 v[36:37], v[36:37], v[160:161] op_sel_hi:[1,0]
	v_pk_mul_f32 v[34:35], v[34:35], v[160:161] op_sel_hi:[1,0]
	v_pk_mul_f32 v[32:33], v[32:33], v[160:161] op_sel_hi:[1,0]
	v_pk_mul_f32 v[14:15], v[14:15], v[160:161] op_sel_hi:[1,0]
	v_pk_mul_f32 v[12:13], v[12:13], v[160:161] op_sel_hi:[1,0]
	v_pk_mul_f32 v[10:11], v[10:11], v[160:161] op_sel_hi:[1,0]
	v_pk_mul_f32 v[8:9], v[8:9], v[160:161] op_sel_hi:[1,0]
	v_pk_mul_f32 v[6:7], v[6:7], v[160:161] op_sel_hi:[1,0]
	v_pk_mul_f32 v[4:5], v[4:5], v[160:161] op_sel_hi:[1,0]
	v_pk_mul_f32 v[2:3], v[2:3], v[160:161] op_sel_hi:[1,0]
	v_pk_mul_f32 v[0:1], v[0:1], v[160:161] op_sel_hi:[1,0]
.LBB0_932:
	v_cndmask_b32_e64 v212, v171, v170, s[2:3]
	s_waitcnt vmcnt(0) lgkmcnt(0)
	s_barrier
	v_mul_f32_e32 v186, 0xbdd53b94, v212
	v_pk_fma_f32 v[184:185], v[80:81], s[20:21], v[186:187] op_sel_hi:[1,0,0]
	v_pk_fma_f32 v[182:183], v[82:83], s[20:21], v[186:187] op_sel_hi:[1,0,0]
	v_pk_fma_f32 v[180:181], v[84:85], s[20:21], v[186:187] op_sel_hi:[1,0,0]
	v_pk_fma_f32 v[178:179], v[86:87], s[20:21], v[186:187] op_sel_hi:[1,0,0]
	v_pk_fma_f32 v[176:177], v[88:89], s[20:21], v[186:187] op_sel_hi:[1,0,0]
	v_pk_fma_f32 v[174:175], v[90:91], s[20:21], v[186:187] op_sel_hi:[1,0,0]
	v_pk_fma_f32 v[172:173], v[92:93], s[20:21], v[186:187] op_sel_hi:[1,0,0]
	v_pk_fma_f32 v[170:171], v[94:95], s[20:21], v[186:187] op_sel_hi:[1,0,0]
	s_cmp_gt_u32 s61, 60
	s_mov_b64 s[2:3], -1
	s_cbranch_scc1 .LBB0_934
	s_lshl_b32 s30, s101, 11
	s_add_i32 s30, s30, s63
	v_lshl_add_u64 v[80:81], v[154:155], 0, s[46:47]
	s_mov_b32 m0, s30
	s_add_i32 s2, s30, 0x4000
	global_load_lds_dwordx4 v[80:81], off
	v_lshl_add_u64 v[82:83], v[156:157], 0, s[48:49]
	s_mov_b32 m0, s2
	s_addk_i32 s30, 0x400
	global_load_lds_dwordx4 v[82:83], off
	v_lshl_add_u64 v[80:81], v[154:155], 0, s[50:51]
	s_mov_b32 m0, s30
	s_addk_i32 s2, 0x400
	global_load_lds_dwordx4 v[80:81], off
	v_lshl_add_u64 v[82:83], v[158:159], 0, s[48:49]
	s_mov_b32 m0, s2
	s_lshl_b32 s30, s101, 10
	s_add_i32 s30, s30, s63
	s_add_i32 s30, s30, 0x8000
	global_load_lds_dwordx4 v[82:83], off
	v_lshl_add_u64 v[80:81], v[152:153], 0, s[52:53]
	s_mov_b32 m0, s30
	v_lshl_add_u64 v[152:153], v[152:153], 0, s[18:19]
	global_load_lds_dwordx4 v[80:81], off
	v_lshl_add_u64 v[154:155], v[154:155], 0, s[16:17]
	v_lshl_add_u64 v[156:157], v[156:157], 0, s[16:17]
	v_lshl_add_u64 v[158:159], v[158:159], 0, s[16:17]
	s_add_i32 s61, s61, 2
	s_mov_b64 s[2:3], 0

; DI u32x4 pack8(const f32x4 v0, const f32x4 v1) { u32x4 w; w.x = cvt_pk_bf16(v0[0], v0[1]); w.y = cvt_pk_bf16(v0[2], v0[3]); w.z = cvt_pk_bf16(v1[0], v1[1]); w.w = cvt_pk_bf16(v1[2], v1[3]); return w; }
;     DI void operator()(const f32x4 (&acc)[2][2][4][2], const Unit& u, int wr, int wc, int fr, int fq) const {
;         const int row0 = u.pm * 256 + wr * 64 + fr, col0 = u.pn * 128 + wc * 32 + 8 * fq;
;         float ssv[8];
; #pragma unroll
;         for (int i = 0; i < 8; ++i) ssv[i] = SS[(size_t)(row0 + (i >> 2) * 128 + (i & 3) * 16)];
; #pragma unroll
;         for (int ai = 0; ai < 2; ++ai)
; #pragma unroll
;             for (int m = 0; m < 4; ++m) {
;                 const size_t row = (size_t)(row0 + ai * 128 + m * 16);
;                 const float rs = __builtin_amdgcn_rsqf(ssv[ai * 4 + m] * (1.0f / 1024.0f) + EPS);
;                 const float c1 = -rs * 1.4426950408889634f, rs2 = rs * rs;
;                 f32x4 o[2];
; #pragma unroll
;                 for (int n = 0; n < 2; ++n)
; #pragma unroll
;                     for (int j = 0; j < 4; ++j) { const float ga = acc[ai][0][m][n][j], ua = acc[ai][1][m][n][j];
;                         o[n][j] = (ga * ua) * (rs2 * __builtin_amdgcn_rcpf(1.0f + __builtin_amdgcn_exp2f(ga * c1))); }
;                 __builtin_nontemporal_store(pack8(o[0], o[1]), (u32x4*)(GU + row * DFF + col0));
;             }
.LBB0_1388:
	v_lshl_add_u32 v144, s42, 8, v146
	v_ashrrev_i32_e32 v145, 31, v144
	v_lshl_add_u64 v[154:155], v[144:145], 2, s[14:15]
	global_load_dword v145, v[154:155], off
	global_load_dword v153, v[154:155], off offset:64
	v_mov_b32_e32 v160, v124
	v_mov_b32_e32 v164, v126
	v_mov_b32_e32 v178, v104
	global_load_dword v182, v[154:155], off offset:128
	global_load_dword v183, v[154:155], off offset:192
	global_load_dword v184, v[154:155], off offset:512
	global_load_dword v126, v[154:155], off offset:576
	global_load_dword v124, v[154:155], off offset:640
	global_load_dword v104, v[154:155], off offset:704
	v_lshl_or_b32 v156, s61, 7, v148
	v_ashrrev_i32_e32 v157, 31, v156
	v_mov_b32_e32 v172, v122
	v_mov_b32_e32 v174, v123
	v_lshlrev_b64 v[122:123], 1, v[156:157]
	v_mov_b32_e32 v158, v116
	v_mov_b32_e32 v176, v108
	v_mov_b32_e32 v168, v120
	v_mov_b32_e32 v170, v121
	v_mov_b64_e32 v[120:121], s[8:9]
	v_mad_i64_i32 v[180:181], s[30:31], v144, s60, v[120:121]
	v_lshl_add_u64 v[154:155], v[180:181], 0, v[122:123]
	v_mov_b32_e32 v162, v125
	v_mov_b32_e32 v166, v127
	v_or_b32_e32 v127, 16, v144
	v_add_u32_e32 v125, 0x80, v144
	s_andn2_b64 vcc, exec, s[4:5]
	s_mov_b64 s[4:5], -1
	s_waitcnt vmcnt(0)
	v_fmamk_f32 v145, v145, 0x3a800000, v152
	v_rsq_f32_e32 v145, v145
	v_fmamk_f32 v153, v153, 0x3a800000, v152
	v_rsq_f32_e32 v153, v153
	v_mul_f32_e32 v156, 0xbfb8aa3b, v145
	v_mul_f32_e32 v159, v145, v145
	v_mul_f32_e32 v145, 0xbfb8aa3b, v153
	v_mul_f32_e32 v116, v116, v156
	v_mul_f32_e32 v177, v153, v153
	v_mul_f32_e32 v153, v117, v156
	v_mul_f32_e32 v161, v119, v156
	v_mul_f32_e32 v163, v112, v156
	v_mul_f32_e32 v167, v114, v156
	v_mul_f32_e32 v108, v108, v145
	v_exp_f32_e32 v116, v116
	v_mul_f32_e32 v157, v118, v156
	v_mul_f32_e32 v169, v109, v145
	v_exp_f32_e32 v153, v153
	v_exp_f32_e32 v161, v161
	v_exp_f32_e32 v163, v163
	v_exp_f32_e32 v167, v167
	v_exp_f32_e32 v108, v108
	v_mul_f32_e32 v165, v113, v156
	v_exp_f32_e32 v157, v157
	v_exp_f32_e32 v169, v169
	v_exp_f32_e32 v165, v165
	v_add_f32_e32 v116, 1.0, v116
	v_add_f32_e32 v153, 1.0, v153
	v_add_f32_e32 v171, 1.0, v161
	v_add_f32_e32 v173, 1.0, v163
	v_add_f32_e32 v179, 1.0, v167
	v_add_f32_e32 v108, 1.0, v108
	v_rcp_f32_e32 v161, v116
	v_mul_f32_e32 v156, v115, v156
	v_add_f32_e32 v157, 1.0, v157
	v_add_f32_e32 v180, 1.0, v169
	v_rcp_f32_e32 v163, v153
	v_rcp_f32_e32 v169, v173
	v_rcp_f32_e32 v173, v179
	v_rcp_f32_e32 v179, v108
	v_exp_f32_e32 v156, v156
	v_add_f32_e32 v175, 1.0, v165
	v_rcp_f32_e32 v165, v157
	v_rcp_f32_e32 v167, v171
	v_mul_f32_e32 v160, v158, v160
	v_mul_f32_e32 v161, v159, v161
	v_mov_b32_e32 v158, v117
	v_rcp_f32_e32 v171, v175
	v_mul_f32_e32 v116, v176, v178
	v_mul_f32_e32 v117, v177, v179
	v_mov_b32_e32 v176, v109
	v_mul_f32_e32 v108, v158, v162
	v_mul_f32_e32 v109, v159, v163
	v_add_f32_e32 v156, 1.0, v156
	v_mul_f32_e32 v116, v116, v117
	v_mul_f32_e32 v117, v108, v109
	v_mul_f32_e32 v108, v118, v164
	v_mul_f32_e32 v109, v159, v165
	v_rcp_f32_e32 v175, v156
	v_mul_f32_e32 v118, v108, v109
	v_mul_f32_e32 v108, v119, v166
	v_mul_f32_e32 v109, v159, v167
	v_mov_b32_e32 v158, v112
	v_mul_f32_e32 v153, v160, v161
	v_cvt_pk_bf16_f32 v112, v153, v117
	v_mul_f32_e32 v117, v108, v109
	v_mul_f32_e32 v108, v158, v168
	v_mul_f32_e32 v109, v159, v169
	v_mul_f32_e32 v119, v108, v109
	v_mul_f32_e32 v108, v113, v170
	v_mul_f32_e32 v109, v159, v171
	v_mov_b32_e32 v158, v114
	v_mul_f32_e32 v114, v108, v109
	v_mul_f32_e32 v108, v158, v172
	v_mul_f32_e32 v109, v159, v173
	v_mov_b32_e32 v158, v115
	v_mul_f32_e32 v115, v108, v109
	v_mul_f32_e32 v108, v158, v174
	v_mul_f32_e32 v109, v159, v175
	v_rcp_f32_e32 v157, v180
	v_mul_f32_e32 v108, v108, v109
	v_cvt_pk_bf16_f32 v115, v115, v108
	v_mul_f32_e32 v108, v110, v145
	v_cvt_pk_bf16_f32 v113, v118, v117
	v_cvt_pk_bf16_f32 v114, v119, v114
	global_store_dwordx4 v[154:155], v[112:115], off nt
	v_mov_b32_e32 v156, v105
	s_nop 0
	v_exp_f32_e32 v112, v108
	v_mul_f32_e32 v108, v176, v105
	v_mul_f32_e32 v109, v177, v157
	v_mov_b32_e32 v176, v110
	v_mul_f32_e32 v105, v108, v109
	v_add_f32_e32 v108, 1.0, v112
	v_rcp_f32_e32 v109, v108
	v_mul_f32_e32 v108, v111, v145
	v_exp_f32_e32 v110, v108
	v_mul_f32_e32 v108, v176, v106
	v_mul_f32_e32 v109, v177, v109
	v_add_f32_e32 v106, 1.0, v110
	v_mul_f32_e32 v112, v108, v109
	v_rcp_f32_e32 v109, v106
	v_mul_f32_e32 v106, v100, v145
	v_exp_f32_e32 v110, v106
	v_mul_f32_e32 v106, v111, v107
	v_mul_f32_e32 v107, v177, v109
	v_mov_b32_e32 v176, v100
	v_mul_f32_e32 v108, v106, v107
	v_add_f32_e32 v106, 1.0, v110
	v_mul_f32_e32 v100, v101, v145
	v_rcp_f32_e32 v107, v106
	v_exp_f32_e32 v100, v100
	v_mul_f32_e32 v106, v176, v96
	v_mul_f32_e32 v107, v177, v107
	v_add_f32_e32 v96, 1.0, v100
	v_mul_f32_e32 v109, v106, v107
	v_rcp_f32_e32 v107, v96
	v_mul_f32_e32 v96, v102, v145
	v_exp_f32_e32 v100, v96
	v_mul_f32_e32 v96, v101, v97
	v_mul_f32_e32 v97, v177, v107
	v_mul_f32_e32 v106, v96, v97
	v_add_f32_e32 v96, 1.0, v100
	v_rcp_f32_e32 v97, v96
	v_mul_f32_e32 v96, v103, v145
	v_exp_f32_e32 v100, v96
	v_mul_f32_e32 v96, v102, v98
	v_mul_f32_e32 v97, v177, v97
	v_mov_b32_e32 v176, v103
	v_add_f32_e32 v98, 1.0, v100
	v_rcp_f32_e32 v101, v98
	v_mul_f32_e32 v102, v96, v97
	v_cvt_pk_bf16_f32 v98, v109, v106
	v_mul_f32_e32 v96, v103, v99
	v_mul_f32_e32 v97, v177, v101
	v_fmamk_f32 v100, v182, 0x3a800000, v152
	v_mul_f32_e32 v99, v96, v97
	v_cvt_pk_bf16_f32 v99, v102, v99
	v_rsq_f32_e32 v102, v100
	v_cvt_pk_bf16_f32 v96, v116, v105
	v_mad_i64_i32 v[100:101], s[30:31], v127, s60, v[120:121]
	v_mul_f32_e32 v103, 0xbfb8aa3b, v102
	v_mul_f32_e32 v105, v92, v103
	v_exp_f32_e32 v105, v105
	v_lshl_add_u64 v[100:101], v[100:101], 0, v[122:123]
; DI u32x4 pack8(const f32x4 v0, const f32x4 v1) { u32x4 w; w.x = cvt_pk_bf16(v0[0], v0[1]); w.y = cvt_pk_bf16(v0[2], v0[3]); w.z = cvt_pk_bf16(v1[0], v1[1]); w.w = cvt_pk_bf16(v1[2], v1[3]); return w; }
;     DI void operator()(const f32x4 (&acc)[2][2][4][2], const Unit& u, int wr, int wc, int fr, int fq) const {
;     ...
;             for (int m = 0; m < 4; ++m) {
;                 const size_t row = (size_t)(row0 + ai * 128 + m * 16);
;                 const float rs = __builtin_amdgcn_rsqf(ssv[ai * 4 + m] * (1.0f / 1024.0f) + EPS);
;                 const float c1 = -rs * 1.4426950408889634f, rs2 = rs * rs;
;                 f32x4 o[2];
; #pragma unroll
;                 for (int n = 0; n < 2; ++n)
; #pragma unroll
;                     for (int j = 0; j < 4; ++j) { const float ga = acc[ai][0][m][n][j], ua = acc[ai][1][m][n][j];
;                         o[n][j] = (ga * ua) * (rs2 * __builtin_amdgcn_rcpf(1.0f + __builtin_amdgcn_exp2f(ga * c1))); }
;                 __builtin_nontemporal_store(pack8(o[0], o[1]), (u32x4*)(GU + row * DFF + col0));
;             }
	v_cvt_pk_bf16_f32 v97, v112, v108
	global_store_dwordx4 v[100:101], v[96:99], off nt
	v_or_b32_e32 v100, 32, v144
	s_nop 0
	v_add_f32_e32 v96, 1.0, v105
	v_rcp_f32_e32 v99, v96
	v_mov_b32_e32 v96, v92
	v_mul_f32_e32 v92, v93, v103
	v_exp_f32_e32 v92, v92
	v_mul_f32_e32 v97, v102, v102
	v_mul_f32_e32 v98, v96, v88
	v_mul_f32_e32 v99, v97, v99
	v_add_f32_e32 v88, 1.0, v92
	v_mul_f32_e32 v101, v98, v99
	v_rcp_f32_e32 v99, v88
	v_mul_f32_e32 v88, v94, v103
	v_exp_f32_e32 v92, v88
	v_mov_b32_e32 v98, v89
	v_mul_f32_e32 v88, v93, v89
	v_mul_f32_e32 v89, v97, v99
	v_mul_f32_e32 v93, v88, v89
	v_add_f32_e32 v88, 1.0, v92
	v_rcp_f32_e32 v89, v88
	v_mul_f32_e32 v88, v95, v103
	v_exp_f32_e32 v92, v88
	v_mul_f32_e32 v88, v94, v90
	v_mul_f32_e32 v89, v97, v89
	v_mul_f32_e32 v90, v88, v89
	v_add_f32_e32 v88, 1.0, v92
	v_rcp_f32_e32 v89, v88
	v_mul_f32_e32 v88, v84, v103
	v_exp_f32_e32 v92, v88
	v_mul_f32_e32 v88, v95, v91
	v_mul_f32_e32 v89, v97, v89
	v_mov_b32_e32 v96, v84
	v_mul_f32_e32 v91, v88, v89
	v_add_f32_e32 v88, 1.0, v92
	v_mul_f32_e32 v84, v85, v103
	v_rcp_f32_e32 v89, v88
	v_exp_f32_e32 v84, v84
	v_mul_f32_e32 v88, v96, v80
	v_mul_f32_e32 v89, v97, v89
	v_add_f32_e32 v80, 1.0, v84
	v_mul_f32_e32 v92, v88, v89
	v_rcp_f32_e32 v89, v80
	v_mul_f32_e32 v80, v86, v103
	v_exp_f32_e32 v84, v80
	v_mul_f32_e32 v80, v85, v81
	v_mul_f32_e32 v81, v97, v89
	v_mul_f32_e32 v88, v80, v81
	v_add_f32_e32 v80, 1.0, v84
	v_rcp_f32_e32 v81, v80
	v_mul_f32_e32 v80, v87, v103
	v_exp_f32_e32 v84, v80
	v_mul_f32_e32 v80, v86, v82
	v_mul_f32_e32 v81, v97, v81
	v_mov_b32_e32 v96, v87
	v_add_f32_e32 v82, 1.0, v84
	v_rcp_f32_e32 v85, v82
	v_mul_f32_e32 v86, v80, v81
	v_cvt_pk_bf16_f32 v82, v92, v88
	v_mul_f32_e32 v80, v87, v83
	v_mul_f32_e32 v81, v97, v85
	v_fmamk_f32 v84, v183, 0x3a800000, v152
	v_mul_f32_e32 v83, v80, v81
	v_cvt_pk_bf16_f32 v83, v86, v83
	v_rsq_f32_e32 v86, v84
	v_mad_i64_i32 v[84:85], s[30:31], v100, s60, v[120:121]
	v_cvt_pk_bf16_f32 v80, v101, v93
	v_mul_f32_e32 v87, 0xbfb8aa3b, v86
	v_mul_f32_e32 v88, v76, v87
	v_exp_f32_e32 v88, v88
	v_lshl_add_u64 v[84:85], v[84:85], 0, v[122:123]
	v_cvt_pk_bf16_f32 v81, v90, v91
	global_store_dwordx4 v[84:85], v[80:83], off nt
	v_or_b32_e32 v84, 48, v144
	s_nop 0
	v_add_f32_e32 v80, 1.0, v88
	v_rcp_f32_e32 v83, v80
	v_mov_b32_e32 v80, v76
	v_mul_f32_e32 v76, v77, v87
	v_exp_f32_e32 v76, v76
	v_mul_f32_e32 v81, v86, v86
	v_mul_f32_e32 v82, v80, v72
	v_mul_f32_e32 v83, v81, v83
	v_add_f32_e32 v72, 1.0, v76
	v_mul_f32_e32 v85, v82, v83
	v_rcp_f32_e32 v83, v72
	v_mul_f32_e32 v72, v78, v87
	v_exp_f32_e32 v76, v72
	v_mov_b32_e32 v82, v73
	v_mul_f32_e32 v72, v77, v73
	v_mul_f32_e32 v73, v81, v83
	v_mul_f32_e32 v77, v72, v73
	v_add_f32_e32 v72, 1.0, v76
	v_rcp_f32_e32 v73, v72
	v_mul_f32_e32 v72, v79, v87
	v_exp_f32_e32 v76, v72
	v_mul_f32_e32 v72, v78, v74
	v_mul_f32_e32 v73, v81, v73
	v_mul_f32_e32 v74, v72, v73
	v_add_f32_e32 v72, 1.0, v76
	v_rcp_f32_e32 v73, v72
	v_mul_f32_e32 v72, v68, v87
	v_exp_f32_e32 v76, v72
	v_mul_f32_e32 v72, v79, v75
	v_mul_f32_e32 v73, v81, v73
	v_mov_b32_e32 v80, v68
	v_mul_f32_e32 v75, v72, v73
	v_add_f32_e32 v72, 1.0, v76
	v_mul_f32_e32 v68, v69, v87
	v_rcp_f32_e32 v73, v72
	v_exp_f32_e32 v68, v68
	v_mul_f32_e32 v72, v80, v64
	v_mul_f32_e32 v73, v81, v73
	v_add_f32_e32 v64, 1.0, v68
	v_mul_f32_e32 v76, v72, v73
	v_rcp_f32_e32 v73, v64
	v_mul_f32_e32 v64, v70, v87
	v_exp_f32_e32 v68, v64
	v_mul_f32_e32 v64, v69, v65
	v_mul_f32_e32 v65, v81, v73
	v_mul_f32_e32 v72, v64, v65
	v_add_f32_e32 v64, 1.0, v68
	v_rcp_f32_e32 v65, v64
	v_mul_f32_e32 v64, v71, v87
	v_exp_f32_e32 v68, v64
	v_mul_f32_e32 v64, v70, v66
	v_mul_f32_e32 v65, v81, v65
	v_mov_b32_e32 v80, v71
	v_add_f32_e32 v66, 1.0, v68
	v_rcp_f32_e32 v69, v66
	v_mul_f32_e32 v70, v64, v65
	v_cvt_pk_bf16_f32 v66, v76, v72
	v_mul_f32_e32 v64, v71, v67
	v_mul_f32_e32 v65, v81, v69
	v_fmamk_f32 v68, v184, 0x3a800000, v152
	v_rsq_f32_e32 v71, v68
	v_mul_f32_e32 v67, v64, v65
	v_cvt_pk_bf16_f32 v67, v70, v67
	v_mad_i64_i32 v[68:69], s[30:31], v84, s60, v[120:121]
	v_mul_f32_e32 v70, 0xbfb8aa3b, v71
	v_mul_f32_e32 v72, v60, v70
	v_exp_f32_e32 v72, v72
	v_cvt_pk_bf16_f32 v64, v85, v77
	v_lshl_add_u64 v[68:69], v[68:69], 0, v[122:123]
	v_cvt_pk_bf16_f32 v65, v74, v75
	global_store_dwordx4 v[68:69], v[64:67], off nt
	s_nop 1
	v_add_f32_e32 v64, 1.0, v72
	v_rcp_f32_e32 v67, v64
	v_mov_b32_e32 v64, v60
	v_mul_f32_e32 v60, v61, v70
	v_exp_f32_e32 v60, v60
	v_mul_f32_e32 v65, v71, v71
	v_mul_f32_e32 v66, v64, v56
	v_mul_f32_e32 v67, v65, v67
	v_add_f32_e32 v56, 1.0, v60
	v_mul_f32_e32 v68, v66, v67
	v_rcp_f32_e32 v67, v56
	v_mul_f32_e32 v56, v62, v70
	v_exp_f32_e32 v60, v56
	v_mov_b32_e32 v66, v57
	v_mul_f32_e32 v56, v61, v57
	v_mul_f32_e32 v57, v65, v67
	v_mul_f32_e32 v61, v56, v57
	v_add_f32_e32 v56, 1.0, v60
	v_rcp_f32_e32 v57, v56
	v_mul_f32_e32 v56, v63, v70
	v_exp_f32_e32 v60, v56
	v_mul_f32_e32 v56, v62, v58
	v_mul_f32_e32 v57, v65, v57
	v_mul_f32_e32 v58, v56, v57
	v_add_f32_e32 v56, 1.0, v60
	v_rcp_f32_e32 v57, v56
	v_mul_f32_e32 v56, v52, v70
	v_exp_f32_e32 v60, v56
	v_mul_f32_e32 v56, v63, v59
	v_mul_f32_e32 v57, v65, v57
	v_mov_b32_e32 v64, v52
	v_mul_f32_e32 v59, v56, v57
	v_add_f32_e32 v56, 1.0, v60
	v_mul_f32_e32 v52, v53, v70
	v_rcp_f32_e32 v57, v56
	v_exp_f32_e32 v52, v52
	v_mul_f32_e32 v56, v64, v48
	v_mul_f32_e32 v57, v65, v57
	v_add_f32_e32 v48, 1.0, v52
	v_mul_f32_e32 v60, v56, v57
	v_rcp_f32_e32 v57, v48
	v_mul_f32_e32 v48, v54, v70
	v_exp_f32_e32 v52, v48
	v_mul_f32_e32 v48, v53, v49
	v_mul_f32_e32 v49, v65, v57
	v_mul_f32_e32 v56, v48, v49
	v_add_f32_e32 v48, 1.0, v52
	v_rcp_f32_e32 v49, v48
	v_mul_f32_e32 v48, v55, v70
; #define PG8_BAR __builtin_amdgcn_s_barrier()
; DI u32x4 pack8(const f32x4 v0, const f32x4 v1) { u32x4 w; w.x = cvt_pk_bf16(v0[0], v0[1]); w.y = cvt_pk_bf16(v0[2], v0[3]); w.z = cvt_pk_bf16(v1[0], v1[1]); w.w = cvt_pk_bf16(v1[2], v1[3]); return w; }
; template <class Epi, class Sched, bool ALIGN_EPI = false, bool SP2 = false>
; __device__ __forceinline__ void gemm_phase(PG8_LAS unsigned char* lds, const Gemm g, const Sched& S, const Epi& E) {
;     ...
;         if (!has_next) break;
; #pragma unroll
;         for (int a = 0; a < 2; ++a)
; #pragma unroll
;             for (int b = 0; b < 2; ++b)
; #pragma unroll
;                 for (int m = 0; m < 4; ++m)
; #pragma unroll
;                     for (int n = 0; n < 2; ++n) acc[a][b][m][n] = (f32x4){0.f, 0.f, 0.f, 0.f};
;         cur = nxt; cA = nA; cB = nB; ++ui;
;         if constexpr (ALIGN_EPI) { if (wr == 1) PG8_BAR; }
;     DI void operator()(const f32x4 (&acc)[2][2][4][2], const Unit& u, int wr, int wc, int fr, int fq) const {
;     ...
;             for (int m = 0; m < 4; ++m) {
;                 const size_t row = (size_t)(row0 + ai * 128 + m * 16);
;                 const float rs = __builtin_amdgcn_rsqf(ssv[ai * 4 + m] * (1.0f / 1024.0f) + EPS);
;                 const float c1 = -rs * 1.4426950408889634f, rs2 = rs * rs;
;                 f32x4 o[2];
; #pragma unroll
;                 for (int n = 0; n < 2; ++n)
; #pragma unroll
;                     for (int j = 0; j < 4; ++j) { const float ga = acc[ai][0][m][n][j], ua = acc[ai][1][m][n][j];
;                         o[n][j] = (ga * ua) * (rs2 * __builtin_amdgcn_rcpf(1.0f + __builtin_amdgcn_exp2f(ga * c1))); }
;                 __builtin_nontemporal_store(pack8(o[0], o[1]), (u32x4*)(GU + row * DFF + col0));
;             }
	v_exp_f32_e32 v52, v48
	v_mul_f32_e32 v48, v54, v50
	v_mul_f32_e32 v49, v65, v49
	v_mov_b32_e32 v64, v55
	v_add_f32_e32 v50, 1.0, v52
	v_rcp_f32_e32 v53, v50
	v_mul_f32_e32 v54, v48, v49
	v_cvt_pk_bf16_f32 v50, v60, v56
	v_mul_f32_e32 v48, v55, v51
	v_mul_f32_e32 v49, v65, v53
	v_fmamk_f32 v52, v126, 0x3a800000, v152
	v_mul_f32_e32 v51, v48, v49
	v_cvt_pk_bf16_f32 v51, v54, v51
	v_rsq_f32_e32 v54, v52
	v_mad_i64_i32 v[52:53], s[30:31], v125, s60, v[120:121]
	v_cvt_pk_bf16_f32 v48, v68, v61
	v_mul_f32_e32 v55, 0xbfb8aa3b, v54
	v_mul_f32_e32 v56, v44, v55
	v_exp_f32_e32 v56, v56
	v_lshl_add_u64 v[52:53], v[52:53], 0, v[122:123]
	v_cvt_pk_bf16_f32 v49, v58, v59
	global_store_dwordx4 v[52:53], v[48:51], off nt
	v_add_u32_e32 v52, 0x90, v144
	s_nop 0
	v_add_f32_e32 v48, 1.0, v56
	v_rcp_f32_e32 v51, v48
	v_mov_b32_e32 v48, v44
	v_mul_f32_e32 v44, v45, v55
	v_exp_f32_e32 v44, v44
	v_mul_f32_e32 v49, v54, v54
	v_mul_f32_e32 v50, v48, v40
	v_mul_f32_e32 v51, v49, v51
	v_add_f32_e32 v40, 1.0, v44
	v_mul_f32_e32 v53, v50, v51
	v_rcp_f32_e32 v51, v40
	v_mul_f32_e32 v40, v46, v55
	v_exp_f32_e32 v44, v40
	v_mov_b32_e32 v50, v41
	v_mul_f32_e32 v40, v45, v41
	v_mul_f32_e32 v41, v49, v51
	v_mul_f32_e32 v45, v40, v41
	v_add_f32_e32 v40, 1.0, v44
	v_rcp_f32_e32 v41, v40
	v_mul_f32_e32 v40, v47, v55
	v_exp_f32_e32 v44, v40
	v_mul_f32_e32 v40, v46, v42
	v_mul_f32_e32 v41, v49, v41
	v_mul_f32_e32 v42, v40, v41
	v_add_f32_e32 v40, 1.0, v44
	v_rcp_f32_e32 v41, v40
	v_mul_f32_e32 v40, v36, v55
	v_exp_f32_e32 v44, v40
	v_mul_f32_e32 v40, v47, v43
	v_mul_f32_e32 v41, v49, v41
	v_mov_b32_e32 v48, v36
	v_mul_f32_e32 v43, v40, v41
	v_add_f32_e32 v40, 1.0, v44
	v_mul_f32_e32 v36, v37, v55
	v_rcp_f32_e32 v41, v40
	v_exp_f32_e32 v36, v36
	v_mul_f32_e32 v40, v48, v32
	v_mul_f32_e32 v41, v49, v41
	v_add_f32_e32 v32, 1.0, v36
	v_mul_f32_e32 v44, v40, v41
	v_rcp_f32_e32 v41, v32
	v_mul_f32_e32 v32, v38, v55
	v_exp_f32_e32 v36, v32
	v_mul_f32_e32 v32, v37, v33
	v_mul_f32_e32 v33, v49, v41
	v_mul_f32_e32 v40, v32, v33
	v_add_f32_e32 v32, 1.0, v36
	v_rcp_f32_e32 v33, v32
	v_mul_f32_e32 v32, v39, v55
	v_exp_f32_e32 v36, v32
	v_mul_f32_e32 v32, v38, v34
	v_mul_f32_e32 v33, v49, v33
	v_mov_b32_e32 v48, v39
	v_add_f32_e32 v34, 1.0, v36
	v_rcp_f32_e32 v37, v34
	v_mul_f32_e32 v38, v32, v33
	v_cvt_pk_bf16_f32 v34, v44, v40
	v_mul_f32_e32 v32, v39, v35
	v_mul_f32_e32 v33, v49, v37
	v_fmamk_f32 v36, v124, 0x3a800000, v152
	v_mul_f32_e32 v35, v32, v33
	v_cvt_pk_bf16_f32 v35, v38, v35
	v_rsq_f32_e32 v38, v36
	v_mad_i64_i32 v[36:37], s[30:31], v52, s60, v[120:121]
	v_cvt_pk_bf16_f32 v32, v53, v45
	v_mul_f32_e32 v39, 0xbfb8aa3b, v38
	v_mul_f32_e32 v40, v28, v39
	v_exp_f32_e32 v40, v40
	v_lshl_add_u64 v[36:37], v[36:37], 0, v[122:123]
	v_cvt_pk_bf16_f32 v33, v42, v43
	global_store_dwordx4 v[36:37], v[32:35], off nt
	v_add_u32_e32 v36, 0xa0, v144
	s_nop 0
	v_add_f32_e32 v32, 1.0, v40
	v_rcp_f32_e32 v35, v32
	v_mov_b32_e32 v32, v28
	v_mul_f32_e32 v28, v29, v39
	v_exp_f32_e32 v28, v28
	v_mul_f32_e32 v33, v38, v38
	v_mul_f32_e32 v34, v32, v24
	v_mul_f32_e32 v35, v33, v35
	v_add_f32_e32 v24, 1.0, v28
	v_mul_f32_e32 v37, v34, v35
	v_rcp_f32_e32 v35, v24
	v_mul_f32_e32 v24, v30, v39
	v_exp_f32_e32 v28, v24
	v_mov_b32_e32 v34, v25
	v_mul_f32_e32 v24, v29, v25
	v_mul_f32_e32 v25, v33, v35
	v_mul_f32_e32 v29, v24, v25
	v_add_f32_e32 v24, 1.0, v28
	v_rcp_f32_e32 v25, v24
	v_mul_f32_e32 v24, v31, v39
	v_exp_f32_e32 v28, v24
	v_mul_f32_e32 v24, v30, v26
	v_mul_f32_e32 v25, v33, v25
	v_mul_f32_e32 v26, v24, v25
	v_add_f32_e32 v24, 1.0, v28
	v_rcp_f32_e32 v25, v24
	v_mul_f32_e32 v24, v20, v39
	v_exp_f32_e32 v28, v24
	v_mul_f32_e32 v24, v31, v27
	v_mul_f32_e32 v25, v33, v25
	v_mov_b32_e32 v32, v20
	v_mul_f32_e32 v27, v24, v25
	v_add_f32_e32 v24, 1.0, v28
	v_mul_f32_e32 v20, v21, v39
	v_rcp_f32_e32 v25, v24
	v_exp_f32_e32 v20, v20
	v_mul_f32_e32 v24, v32, v16
	v_mul_f32_e32 v25, v33, v25
	v_add_f32_e32 v16, 1.0, v20
	v_mul_f32_e32 v28, v24, v25
	v_rcp_f32_e32 v25, v16
	v_mul_f32_e32 v16, v22, v39
	v_exp_f32_e32 v20, v16
	v_mul_f32_e32 v16, v21, v17
	v_mul_f32_e32 v17, v33, v25
	v_mul_f32_e32 v24, v16, v17
	v_add_f32_e32 v16, 1.0, v20
	v_rcp_f32_e32 v17, v16
	v_mul_f32_e32 v16, v23, v39
	v_exp_f32_e32 v20, v16
	v_mul_f32_e32 v16, v22, v18
	v_mul_f32_e32 v17, v33, v17
	v_mov_b32_e32 v32, v23
	v_add_f32_e32 v18, 1.0, v20
	v_rcp_f32_e32 v21, v18
	v_mul_f32_e32 v22, v16, v17
	v_cvt_pk_bf16_f32 v18, v28, v24
	v_mul_f32_e32 v16, v23, v19
	v_mul_f32_e32 v17, v33, v21
	v_fmamk_f32 v20, v104, 0x3a800000, v152
	v_mul_f32_e32 v19, v16, v17
	v_cvt_pk_bf16_f32 v19, v22, v19
	v_rsq_f32_e32 v22, v20
	v_mad_i64_i32 v[20:21], s[30:31], v36, s60, v[120:121]
	v_cvt_pk_bf16_f32 v16, v37, v29
	v_mul_f32_e32 v23, 0xbfb8aa3b, v22
	v_mul_f32_e32 v24, v12, v23
	v_exp_f32_e32 v24, v24
	v_lshl_add_u64 v[20:21], v[20:21], 0, v[122:123]
	v_cvt_pk_bf16_f32 v17, v26, v27
	global_store_dwordx4 v[20:21], v[16:19], off nt
	v_add_u32_e32 v20, 0xb0, v144
	s_nop 0
	v_add_f32_e32 v16, 1.0, v24
	v_rcp_f32_e32 v19, v16
	v_mov_b32_e32 v16, v12
	v_mul_f32_e32 v12, v13, v23
	v_exp_f32_e32 v12, v12
	v_mul_f32_e32 v17, v22, v22
	v_mul_f32_e32 v18, v16, v8
	v_mul_f32_e32 v19, v17, v19
	v_add_f32_e32 v8, 1.0, v12
	v_mul_f32_e32 v21, v18, v19
	v_rcp_f32_e32 v19, v8
	v_mul_f32_e32 v8, v14, v23
	v_exp_f32_e32 v12, v8
	v_mov_b32_e32 v18, v9
	v_mul_f32_e32 v8, v13, v9
	v_mul_f32_e32 v9, v17, v19
	v_mul_f32_e32 v13, v8, v9
	v_add_f32_e32 v8, 1.0, v12
	v_rcp_f32_e32 v9, v8
	v_mul_f32_e32 v8, v15, v23
	v_exp_f32_e32 v12, v8
	v_mul_f32_e32 v8, v14, v10
	v_mul_f32_e32 v9, v17, v9
	v_mul_f32_e32 v10, v8, v9
	v_add_f32_e32 v8, 1.0, v12
	v_rcp_f32_e32 v9, v8
	v_mul_f32_e32 v8, v4, v23
	v_exp_f32_e32 v12, v8
	v_mul_f32_e32 v8, v15, v11
	v_mul_f32_e32 v9, v17, v9
	v_mov_b32_e32 v16, v4
	v_mul_f32_e32 v11, v8, v9
	v_add_f32_e32 v8, 1.0, v12
	v_mul_f32_e32 v4, v5, v23
	v_rcp_f32_e32 v9, v8
	v_exp_f32_e32 v4, v4
	v_mul_f32_e32 v8, v16, v0
	v_mul_f32_e32 v9, v17, v9
	v_add_f32_e32 v0, 1.0, v4
	v_mul_f32_e32 v12, v8, v9
	v_rcp_f32_e32 v9, v0
	v_mul_f32_e32 v0, v6, v23
	v_exp_f32_e32 v4, v0
	v_mul_f32_e32 v0, v5, v1
	v_mul_f32_e32 v1, v17, v9
	v_mul_f32_e32 v8, v0, v1
	v_add_f32_e32 v0, 1.0, v4
	v_rcp_f32_e32 v1, v0
	v_mul_f32_e32 v0, v7, v23
	v_exp_f32_e32 v4, v0
	v_mul_f32_e32 v0, v6, v2
	v_mul_f32_e32 v1, v17, v1
	v_mov_b32_e32 v16, v7
	v_add_f32_e32 v2, 1.0, v4
	v_rcp_f32_e32 v5, v2
	v_mul_f32_e32 v6, v0, v1
	v_cvt_pk_bf16_f32 v2, v12, v8
	v_mul_f32_e32 v0, v7, v3
	v_mul_f32_e32 v1, v17, v5
	v_mad_i64_i32 v[4:5], s[30:31], v20, s60, v[120:121]
	v_mul_f32_e32 v3, v0, v1
	v_lshl_add_u64 v[4:5], v[4:5], 0, v[122:123]
	v_cvt_pk_bf16_f32 v0, v21, v13
	v_cvt_pk_bf16_f32 v1, v10, v11
	v_cvt_pk_bf16_f32 v3, v6, v3
	global_store_dwordx4 v[4:5], v[0:3], off nt
	s_cbranch_vccnz .LBB0_1381
	s_andn2_b64 vcc, exec, s[6:7]
	s_cbranch_vccnz .LBB0_1380
	s_barrier
	s_branch .LBB0_1380
